# P0 weight transpose rewritten: dwordx4 loads, swizzled LDS, next-item prefetch
# speedup vs baseline: 1.0009x; 1.0009x over previous
; #define LAS __attribute__((address_space(3)))
; __device__ __forceinline__ unsigned pk2(float lo, float hi) { unsigned r; asm("v_cvt_pk_bf16_f32 %0, %1, %2" : "=v"(r) : "v"(lo), "v"(hi)); return r; }
; __device__ __forceinline__ void p0_transpose_item(const float* W, int K, int N, bf16_t* WT, int k0, int n0, int drow0, LAS float* scr, int lane, const float* kscale = nullptr) {
;     const float ks = kscale ? kscale[k0 + lane] : 1.f;
; #pragma unroll 8
;     for (int i = 0; i < 32; ++i) { const int kk = 2 * i + (lane >> 5); scr[kk * 33 + (lane & 31)] = W[(size_t)(k0 + kk) * N + n0 + (lane & 31)] * __shfl(ks, kk); }
;     asm volatile("s_waitcnt lgkmcnt(0)" ::: "memory");
;     const int c = lane & 7;
; #pragma unroll
;     for (int j = 0; j < 4; ++j) { const int n = (lane >> 3) + 8 * j; const LAS float* s = scr + (8 * c) * 33 + n;
;         u32x4 o; o.x = pk2(s[0 * 33], s[1 * 33]); o.y = pk2(s[2 * 33], s[3 * 33]); o.z = pk2(s[4 * 33], s[5 * 33]); o.w = pk2(s[6 * 33], s[7 * 33]);
;         *(u32x4*)(WT + (size_t)(drow0 + n) * K + k0 + 8 * c) = o; }
;     asm volatile("s_waitcnt lgkmcnt(0)" ::: "memory");
; }
; __device__ __forceinline__ int win_dest_row(int n0) {
;     if (n0 < 5120) return n0;
;     if (n0 < 5152) return CDT + (n0 - 5120);
;     if (n0 < 7200) { const int c = n0 - 5152; return CCF + 256 * (c >> 7) + (c & 127); }
;     { const int c = n0 - 7200; return CCF + 256 * (c >> 7) + 128 + (c & 127); }
; }
; __global__ void __launch_bounds__(512, 2) mk_fwd(Args args) {
;     ...
;         for (int it = gw; it < n_items0; it += NGW) {
;             int r = it;
;             if (r < I_IN) { const int nblk = 9248 / 32, kb = r / nblk, nb = r % nblk; p0_transpose_item(w_in, DM, 9248, WinT, 64 * kb, 32 * nb, win_dest_row(32 * nb), scr, lane); continue; } r -= I_IN;
;             if (r < I_OUT) { const int nblk = DM / 32, kb = r / nblk, nb = r % nblk; p0_transpose_item(w_out, DMIX, DM, WoutT, 64 * kb, 32 * nb, 32 * nb, scr, lane); continue; } r -= I_OUT;
;             if (r < I_UP) { const int nblk = FF2 / 32, kb = r / nblk, nb = r % nblk; p0_transpose_item(w_up, DM, FF2, WupT, 64 * kb, 32 * nb, 32 * nb, scr, lane, norm_ffn_w); continue; } r -= I_UP;
;             { const int nblk = DM / 32, kb = r / nblk, nb = r % nblk; p0_transpose_item(w_down, FF, DM, WdnT, 64 * kb, 32 * nb, 32 * nb, scr, lane); }
;         }
.LBB0_18:
	s_cmp_lt_i32 s88, 1
	s_cselect_b64 s[0:1], -1, 0
	s_cmp_gt_i32 s89, 0
	s_cselect_b64 s[4:5], -1, 0
	s_and_b64 s[0:1], s[0:1], s[4:5]
	s_andn2_b64 vcc, exec, s[0:1]
	s_cbranch_vccnz .LBB0_61
	s_mov_b64 s[8:9], s[96:97]
	v_mov_b32_e32 v1, v212
	s_lshl_b32 s10, s94, 3
	v_readfirstlane_b32 s3, v1
	s_ashr_i32 s4, s3, 6
	s_lshl_b32 s3, s2, 3
	v_and_b32_e32 v3, 63, v1
	s_add_i32 s3, s4, s3
	s_cmpk_gt_i32 s3, 0x749f
	v_lshlrev_b32_e32 v0, 3, v3
	s_cbranch_scc1 .LBB0_54
	s_load_dwordx2 s[12:13], s[8:9], 0x38
	s_load_dwordx2 s[14:15], s[8:9], 0x90
	s_load_dwordx2 s[16:17], s[8:9], 0xa0
	s_load_dwordx2 s[18:19], s[8:9], 0xb8
	s_load_dwordx2 s[20:21], s[8:9], 0x98
	s_load_dwordx2 s[22:23], s[8:9], 0xd0
	v_lshrrev_b32_e32 v4, 3, v3
	v_and_b32_e32 v7, 7, v3
	v_lshlrev_b32_e32 v5, 4, v7
	v_lshlrev_b32_e32 v6, 5, v7
	s_lshl_b32 s24, s4, 14
	v_lshl_add_u32 v16, v4, 7, s24
	v_xor_b32_e32 v8, 0, v7
	v_lshl_add_u32 v8, v8, 4, v16
	v_xor_b32_e32 v9, 1, v7
	v_lshl_add_u32 v9, v9, 4, v16
	v_xor_b32_e32 v10, 2, v7
	v_lshl_add_u32 v10, v10, 4, v16
	v_xor_b32_e32 v11, 3, v7
	v_lshl_add_u32 v11, v11, 4, v16
	v_xor_b32_e32 v12, 4, v7
	v_lshl_add_u32 v12, v12, 4, v16
	v_xor_b32_e32 v13, 5, v7
	v_lshl_add_u32 v13, v13, 4, v16
	v_xor_b32_e32 v14, 6, v7
	v_lshl_add_u32 v14, v14, 4, v16
	v_xor_b32_e32 v15, 7, v7
	v_lshl_add_u32 v15, v15, 4, v16
	v_lshlrev_b32_e32 v20, 2, v7
	v_lshl_add_u32 v21, v7, 10, s24
	v_add_u32_e32 v16, 0, v4
	v_xor_b32_e32 v16, v16, v20
	v_lshl_add_u32 v16, v16, 2, v21
	v_add_u32_e32 v17, 8, v4
	v_xor_b32_e32 v17, v17, v20
	v_lshl_add_u32 v17, v17, 2, v21
	v_add_u32_e32 v18, 16, v4
	v_xor_b32_e32 v18, v18, v20
	v_lshl_add_u32 v18, v18, 2, v21
	v_add_u32_e32 v19, 24, v4
	v_xor_b32_e32 v19, v19, v20
	v_lshl_add_u32 v19, v19, 2, v21
	s_mov_b32 s11, s3
	s_waitcnt lgkmcnt(0)
	s_cmpk_lt_u32 s11, 9248
	s_cbranch_scc0 .Lp0t_pro_notin
	s_mul_hi_u32 s40, s11, 14861479
	s_mul_i32 s42, s40, 289
	s_sub_u32 s41, s11, s42
	s_mul_i32 s42, s40, 2367488
	s_lshl_b32 s43, s41, 7
	s_add_u32 s42, s42, s43
	s_add_u32 s26, s12, s42
	s_addc_u32 s27, s13, 0
	s_mov_b32 s28, 36992
	s_lshl_b32 s45, s41, 5
	s_mov_b32 s46, s45
	s_cmpk_lt_u32 s45, 5120
	s_cbranch_scc1 .Lp0t_pro_drow_done
	s_movk_i32 s46, 9216
	s_cmpk_lt_u32 s45, 5152
	s_cbranch_scc1 .Lp0t_pro_drow_done
	s_sub_u32 s47, s45, 5152
	s_movk_i32 s43, 5120
	s_cmpk_lt_u32 s45, 7200
	s_cbranch_scc1 .Lp0t_pro_drow_cf
	s_sub_u32 s47, s45, 7200
	s_movk_i32 s43, 5248
.Lp0t_pro_drow_cf:
	s_lshr_b32 s46, s47, 7
	s_lshl_b32 s46, s46, 8
	s_and_b32 s47, s47, 127
	s_add_u32 s46, s46, s47
	s_add_u32 s46, s46, s43
.Lp0t_pro_drow_done:
	s_lshl_b32 s42, s46, 12
	s_lshl_b32 s43, s40, 7
	s_add_u32 s42, s42, s43
	s_add_u32 s30, s22, s42
	s_addc_u32 s31, s23, 0
	s_movk_i32 s32, 4096
	s_mov_b32 s33, 0
	s_branch .Lp0t_pro_decoded
.Lp0t_pro_notin:
	s_sub_u32 s44, s11, 9248
	s_cmpk_lt_u32 s44, 4096
	s_cbranch_scc0 .Lp0t_pro_notout
	s_lshr_b32 s40, s44, 6
	s_and_b32 s41, s44, 63
	s_lshl_b32 s42, s40, 19
	s_lshl_b32 s43, s41, 7
	s_add_u32 s42, s42, s43
	s_add_u32 s26, s14, s42
	s_addc_u32 s27, s15, 0
	s_movk_i32 s28, 8192
	s_lshl_b32 s42, s41, 18
	s_lshl_b32 s43, s40, 7
	s_add_u32 s42, s42, s43
	s_add_u32 s42, s42, 0x2500000
	s_add_u32 s30, s22, s42
	s_addc_u32 s31, s23, 0
	s_movk_i32 s32, 8192
	s_mov_b32 s33, 0
	s_branch .Lp0t_pro_decoded
.Lp0t_pro_notout:
	s_sub_u32 s44, s44, 4096
	s_cmpk_lt_u32 s44, 11008
	s_cbranch_scc0 .Lp0t_pro_notup
	s_mul_hi_u32 s40, s44, 12485371
	s_mul_i32 s42, s40, 344
	s_sub_u32 s41, s44, s42
	s_mul_i32 s42, s40, 2818048
	s_lshl_b32 s43, s41, 7
	s_add_u32 s42, s42, s43
	s_add_u32 s26, s16, s42
	s_addc_u32 s27, s17, 0
	s_mov_b32 s28, 44032
	s_lshl_b32 s42, s41, 17
	s_lshl_b32 s43, s40, 7
	s_add_u32 s42, s42, s43
	s_add_u32 s42, s42, 0x3500000
	s_add_u32 s30, s22, s42
	s_addc_u32 s31, s23, 0
	s_movk_i32 s32, 4096
	s_lshl_b32 s42, s40, 8
	s_add_u32 s34, s20, s42
	s_addc_u32 s35, s21, 0
	s_mov_b32 s33, 1
	s_branch .Lp0t_pro_decoded
.Lp0t_pro_notup:
	s_sub_u32 s44, s44, 11008
	s_lshr_b32 s40, s44, 6
	s_and_b32 s41, s44, 63
	s_lshl_b32 s42, s40, 19
	s_lshl_b32 s43, s41, 7
	s_add_u32 s42, s42, s43
	s_add_u32 s26, s18, s42
	s_addc_u32 s27, s19, 0
	s_movk_i32 s28, 8192
	s_mul_i32 s42, s41, 352256
	s_lshl_b32 s43, s40, 7
	s_add_u32 s42, s42, s43
	s_add_u32 s42, s42, 0x6000000
	s_add_u32 s30, s22, s42
	s_addc_u32 s31, s23, 0
	s_movk_i32 s32, 11008
	s_mov_b32 s33, 0
.Lp0t_pro_decoded:
	v_mad_u32_u24 v20, v4, s28, v5
	s_lshl_b32 s29, s28, 3
	s_cmp_eq_u32 s33, 0
	s_cbranch_scc1 .Lp0t_pro_noscale
	global_load_dwordx4 v[32:35], v6, s[34:35]
	global_load_dwordx4 v[36:39], v6, s[34:35] offset:16
	s_branch .Lp0t_pro_scaled
.Lp0t_pro_noscale:
	v_mov_b32_e32 v32, 1.0
	v_mov_b32_e32 v33, 1.0
	v_mov_b32_e32 v34, 1.0
	v_mov_b32_e32 v35, 1.0
	v_mov_b32_e32 v36, 1.0
	v_mov_b32_e32 v37, 1.0
	v_mov_b32_e32 v38, 1.0
	v_mov_b32_e32 v39, 1.0
.Lp0t_pro_scaled:
	global_load_dwordx4 v[40:43], v20, s[26:27]
	s_add_u32 s26, s26, s29
	s_addc_u32 s27, s27, 0
	global_load_dwordx4 v[44:47], v20, s[26:27]
	s_add_u32 s26, s26, s29
	s_addc_u32 s27, s27, 0
	global_load_dwordx4 v[48:51], v20, s[26:27]
	s_add_u32 s26, s26, s29
	s_addc_u32 s27, s27, 0
	global_load_dwordx4 v[52:55], v20, s[26:27]
	s_add_u32 s26, s26, s29
	s_addc_u32 s27, s27, 0
	global_load_dwordx4 v[56:59], v20, s[26:27]
	s_add_u32 s26, s26, s29
	s_addc_u32 s27, s27, 0
	global_load_dwordx4 v[60:63], v20, s[26:27]
	s_add_u32 s26, s26, s29
	s_addc_u32 s27, s27, 0
	global_load_dwordx4 v[64:67], v20, s[26:27]
	s_add_u32 s26, s26, s29
	s_addc_u32 s27, s27, 0
	global_load_dwordx4 v[68:71], v20, s[26:27]
	s_waitcnt vmcnt(0)
	ds_write_b128 v8, v[40:43] offset:0
	ds_write_b128 v9, v[44:47] offset:1024
	ds_write_b128 v10, v[48:51] offset:2048
	ds_write_b128 v11, v[52:55] offset:3072
	ds_write_b128 v12, v[56:59] offset:4096
	ds_write_b128 v13, v[60:63] offset:5120
	ds_write_b128 v14, v[64:67] offset:6144
	ds_write_b128 v15, v[68:71] offset:7168
	v_mov_b32_e32 v24, v32
	v_mov_b32_e32 v25, v33
	v_mov_b32_e32 v26, v34
	v_mov_b32_e32 v27, v35
	v_mov_b32_e32 v28, v36
	v_mov_b32_e32 v29, v37
	v_mov_b32_e32 v30, v38
	v_mov_b32_e32 v31, v39
	s_mov_b64 s[36:37], s[30:31]
	s_mov_b32 s38, s32
	s_waitcnt lgkmcnt(0)
	s_add_u32 s11, s11, s10
.Lp0t_loop:
	s_cmpk_lt_u32 s11, 29856
	s_cbranch_scc0 .Lp0t_last
	s_cmpk_lt_u32 s11, 9248
	s_cbranch_scc0 .Lp0t_main_notin
	s_mul_hi_u32 s40, s11, 14861479
	s_mul_i32 s42, s40, 289
	s_sub_u32 s41, s11, s42
	s_mul_i32 s42, s40, 2367488
	s_lshl_b32 s43, s41, 7
	s_add_u32 s42, s42, s43
	s_add_u32 s26, s12, s42
	s_addc_u32 s27, s13, 0
	s_mov_b32 s28, 36992
	s_lshl_b32 s45, s41, 5
	s_mov_b32 s46, s45
	s_cmpk_lt_u32 s45, 5120
	s_cbranch_scc1 .Lp0t_main_drow_done
	s_movk_i32 s46, 9216
	s_cmpk_lt_u32 s45, 5152
	s_cbranch_scc1 .Lp0t_main_drow_done
	s_sub_u32 s47, s45, 5152
	s_movk_i32 s43, 5120
	s_cmpk_lt_u32 s45, 7200
	s_cbranch_scc1 .Lp0t_main_drow_cf
	s_sub_u32 s47, s45, 7200
	s_movk_i32 s43, 5248

; #define LAS __attribute__((address_space(3)))
; __device__ __forceinline__ unsigned pk2(float lo, float hi) { unsigned r; asm("v_cvt_pk_bf16_f32 %0, %1, %2" : "=v"(r) : "v"(lo), "v"(hi)); return r; }
; __device__ __forceinline__ void p0_transpose_item(const float* W, int K, int N, bf16_t* WT, int k0, int n0, int drow0, LAS float* scr, int lane, const float* kscale = nullptr) {
;     const float ks = kscale ? kscale[k0 + lane] : 1.f;
; #pragma unroll 8
;     for (int i = 0; i < 32; ++i) { const int kk = 2 * i + (lane >> 5); scr[kk * 33 + (lane & 31)] = W[(size_t)(k0 + kk) * N + n0 + (lane & 31)] * __shfl(ks, kk); }
;     asm volatile("s_waitcnt lgkmcnt(0)" ::: "memory");
;     const int c = lane & 7;
; #pragma unroll
;     for (int j = 0; j < 4; ++j) { const int n = (lane >> 3) + 8 * j; const LAS float* s = scr + (8 * c) * 33 + n;
;         u32x4 o; o.x = pk2(s[0 * 33], s[1 * 33]); o.y = pk2(s[2 * 33], s[3 * 33]); o.z = pk2(s[4 * 33], s[5 * 33]); o.w = pk2(s[6 * 33], s[7 * 33]);
;         *(u32x4*)(WT + (size_t)(drow0 + n) * K + k0 + 8 * c) = o; }
;     asm volatile("s_waitcnt lgkmcnt(0)" ::: "memory");
; }
.Lp0t_main_scaled:
	global_load_dwordx4 v[40:43], v20, s[26:27]
	s_add_u32 s26, s26, s29
	s_addc_u32 s27, s27, 0
	global_load_dwordx4 v[44:47], v20, s[26:27]
	s_add_u32 s26, s26, s29
	s_addc_u32 s27, s27, 0
	global_load_dwordx4 v[48:51], v20, s[26:27]
	s_add_u32 s26, s26, s29
	s_addc_u32 s27, s27, 0
	global_load_dwordx4 v[52:55], v20, s[26:27]
	s_add_u32 s26, s26, s29
	s_addc_u32 s27, s27, 0
	global_load_dwordx4 v[56:59], v20, s[26:27]
	s_add_u32 s26, s26, s29
	s_addc_u32 s27, s27, 0
	global_load_dwordx4 v[60:63], v20, s[26:27]
	s_add_u32 s26, s26, s29
	s_addc_u32 s27, s27, 0
	global_load_dwordx4 v[64:67], v20, s[26:27]
	s_add_u32 s26, s26, s29
	s_addc_u32 s27, s27, 0
	global_load_dwordx4 v[68:71], v20, s[26:27]
	ds_read2_b32 v[72:73], v16 offset0:0 offset1:32
	ds_read2_b32 v[74:75], v16 offset0:64 offset1:96
	ds_read2_b32 v[76:77], v16 offset0:128 offset1:160
	ds_read2_b32 v[78:79], v16 offset0:192 offset1:224
	ds_read2_b32 v[80:81], v17 offset0:0 offset1:32
	ds_read2_b32 v[82:83], v17 offset0:64 offset1:96
	ds_read2_b32 v[84:85], v17 offset0:128 offset1:160
	ds_read2_b32 v[86:87], v17 offset0:192 offset1:224
	ds_read2_b32 v[88:89], v18 offset0:0 offset1:32
	ds_read2_b32 v[90:91], v18 offset0:64 offset1:96
	ds_read2_b32 v[92:93], v18 offset0:128 offset1:160
	ds_read2_b32 v[94:95], v18 offset0:192 offset1:224
	v_mad_u32_u24 v21, v4, s38, v5
	s_lshl_b32 s39, s38, 3
	ds_read2_b32 v[96:97], v19 offset0:0 offset1:32
	ds_read2_b32 v[98:99], v19 offset0:64 offset1:96
	ds_read2_b32 v[100:101], v19 offset0:128 offset1:160
	ds_read2_b32 v[102:103], v19 offset0:192 offset1:224
	s_waitcnt lgkmcnt(12)
	v_mul_f32_e32 v72, v72, v24
	v_mul_f32_e32 v73, v73, v25
	v_mul_f32_e32 v74, v74, v26
	v_mul_f32_e32 v75, v75, v27
	v_mul_f32_e32 v76, v76, v28
	v_mul_f32_e32 v77, v77, v29
	v_mul_f32_e32 v78, v78, v30
	v_mul_f32_e32 v79, v79, v31
	v_cvt_pk_bf16_f32 v72, v72, v73
	v_cvt_pk_bf16_f32 v73, v74, v75
	v_cvt_pk_bf16_f32 v74, v76, v77
	v_cvt_pk_bf16_f32 v75, v78, v79
	global_store_dwordx4 v21, v[72:75], s[36:37]
	s_add_u32 s36, s36, s39
	s_addc_u32 s37, s37, 0
	s_waitcnt lgkmcnt(8)
	v_mul_f32_e32 v80, v80, v24
	v_mul_f32_e32 v81, v81, v25
	v_mul_f32_e32 v82, v82, v26
	v_mul_f32_e32 v83, v83, v27
	v_mul_f32_e32 v84, v84, v28
	v_mul_f32_e32 v85, v85, v29
	v_mul_f32_e32 v86, v86, v30
	v_mul_f32_e32 v87, v87, v31
	v_cvt_pk_bf16_f32 v80, v80, v81
	v_cvt_pk_bf16_f32 v81, v82, v83
	v_cvt_pk_bf16_f32 v82, v84, v85
	v_cvt_pk_bf16_f32 v83, v86, v87
	global_store_dwordx4 v21, v[80:83], s[36:37]
	s_add_u32 s36, s36, s39
	s_addc_u32 s37, s37, 0
	s_waitcnt lgkmcnt(4)
	v_mul_f32_e32 v88, v88, v24
	v_mul_f32_e32 v89, v89, v25
	v_mul_f32_e32 v90, v90, v26
	v_mul_f32_e32 v91, v91, v27
	v_mul_f32_e32 v92, v92, v28
	v_mul_f32_e32 v93, v93, v29
	v_mul_f32_e32 v94, v94, v30
	v_mul_f32_e32 v95, v95, v31
	v_cvt_pk_bf16_f32 v88, v88, v89
	v_cvt_pk_bf16_f32 v89, v90, v91
	v_cvt_pk_bf16_f32 v90, v92, v93
	v_cvt_pk_bf16_f32 v91, v94, v95
	global_store_dwordx4 v21, v[88:91], s[36:37]
	s_add_u32 s36, s36, s39
	s_addc_u32 s37, s37, 0
	s_waitcnt lgkmcnt(0)
	v_mul_f32_e32 v96, v96, v24
	v_mul_f32_e32 v97, v97, v25
	v_mul_f32_e32 v98, v98, v26
	v_mul_f32_e32 v99, v99, v27
	v_mul_f32_e32 v100, v100, v28
	v_mul_f32_e32 v101, v101, v29
	v_mul_f32_e32 v102, v102, v30
	v_mul_f32_e32 v103, v103, v31
	v_cvt_pk_bf16_f32 v96, v96, v97
	v_cvt_pk_bf16_f32 v97, v98, v99
	v_cvt_pk_bf16_f32 v98, v100, v101
	v_cvt_pk_bf16_f32 v99, v102, v103
	global_store_dwordx4 v21, v[96:99], s[36:37]
	s_waitcnt vmcnt(4)
	ds_write_b128 v8, v[40:43] offset:0
	ds_write_b128 v9, v[44:47] offset:1024
	ds_write_b128 v10, v[48:51] offset:2048
	ds_write_b128 v11, v[52:55] offset:3072
	ds_write_b128 v12, v[56:59] offset:4096
	ds_write_b128 v13, v[60:63] offset:5120
	ds_write_b128 v14, v[64:67] offset:6144
	ds_write_b128 v15, v[68:71] offset:7168
	v_mov_b32_e32 v24, v32
	v_mov_b32_e32 v25, v33
	v_mov_b32_e32 v26, v34
	v_mov_b32_e32 v27, v35
	v_mov_b32_e32 v28, v36
	v_mov_b32_e32 v29, v37
	v_mov_b32_e32 v30, v38
	v_mov_b32_e32 v31, v39
	s_mov_b64 s[36:37], s[30:31]
	s_mov_b32 s38, s32
	s_waitcnt lgkmcnt(0)
	s_add_u32 s11, s11, s10
	s_branch .Lp0t_loop
.Lp0t_last:
	ds_read2_b32 v[72:73], v16 offset0:0 offset1:32
	ds_read2_b32 v[74:75], v16 offset0:64 offset1:96
	ds_read2_b32 v[76:77], v16 offset0:128 offset1:160
	ds_read2_b32 v[78:79], v16 offset0:192 offset1:224
	ds_read2_b32 v[80:81], v17 offset0:0 offset1:32
	ds_read2_b32 v[82:83], v17 offset0:64 offset1:96
	ds_read2_b32 v[84:85], v17 offset0:128 offset1:160
	ds_read2_b32 v[86:87], v17 offset0:192 offset1:224
	ds_read2_b32 v[88:89], v18 offset0:0 offset1:32
	ds_read2_b32 v[90:91], v18 offset0:64 offset1:96
	ds_read2_b32 v[92:93], v18 offset0:128 offset1:160
	ds_read2_b32 v[94:95], v18 offset0:192 offset1:224
	v_mad_u32_u24 v21, v4, s38, v5
	s_lshl_b32 s39, s38, 3
	ds_read2_b32 v[96:97], v19 offset0:0 offset1:32
	ds_read2_b32 v[98:99], v19 offset0:64 offset1:96
	ds_read2_b32 v[100:101], v19 offset0:128 offset1:160
	ds_read2_b32 v[102:103], v19 offset0:192 offset1:224
	s_waitcnt lgkmcnt(12)
	v_mul_f32_e32 v72, v72, v24
	v_mul_f32_e32 v73, v73, v25
	v_mul_f32_e32 v74, v74, v26
	v_mul_f32_e32 v75, v75, v27
	v_mul_f32_e32 v76, v76, v28
	v_mul_f32_e32 v77, v77, v29
	v_mul_f32_e32 v78, v78, v30
	v_mul_f32_e32 v79, v79, v31
	v_cvt_pk_bf16_f32 v72, v72, v73
	v_cvt_pk_bf16_f32 v73, v74, v75
	v_cvt_pk_bf16_f32 v74, v76, v77
	v_cvt_pk_bf16_f32 v75, v78, v79
	global_store_dwordx4 v21, v[72:75], s[36:37]
	s_add_u32 s36, s36, s39
	s_addc_u32 s37, s37, 0
	s_waitcnt lgkmcnt(8)
	v_mul_f32_e32 v80, v80, v24
	v_mul_f32_e32 v81, v81, v25
	v_mul_f32_e32 v82, v82, v26
	v_mul_f32_e32 v83, v83, v27
	v_mul_f32_e32 v84, v84, v28
	v_mul_f32_e32 v85, v85, v29
	v_mul_f32_e32 v86, v86, v30
	v_mul_f32_e32 v87, v87, v31
	v_cvt_pk_bf16_f32 v80, v80, v81
	v_cvt_pk_bf16_f32 v81, v82, v83
	v_cvt_pk_bf16_f32 v82, v84, v85
	v_cvt_pk_bf16_f32 v83, v86, v87
	global_store_dwordx4 v21, v[80:83], s[36:37]
	s_add_u32 s36, s36, s39
	s_addc_u32 s37, s37, 0
	s_waitcnt lgkmcnt(4)
	v_mul_f32_e32 v88, v88, v24
	v_mul_f32_e32 v89, v89, v25
	v_mul_f32_e32 v90, v90, v26
	v_mul_f32_e32 v91, v91, v27
	v_mul_f32_e32 v92, v92, v28
	v_mul_f32_e32 v93, v93, v29
	v_mul_f32_e32 v94, v94, v30
	v_mul_f32_e32 v95, v95, v31
	v_cvt_pk_bf16_f32 v88, v88, v89
	v_cvt_pk_bf16_f32 v89, v90, v91
	v_cvt_pk_bf16_f32 v90, v92, v93
	v_cvt_pk_bf16_f32 v91, v94, v95
	global_store_dwordx4 v21, v[88:91], s[36:37]
	s_add_u32 s36, s36, s39
	s_addc_u32 s37, s37, 0
	s_waitcnt lgkmcnt(0)
	v_mul_f32_e32 v96, v96, v24
	v_mul_f32_e32 v97, v97, v25
	v_mul_f32_e32 v98, v98, v26
	v_mul_f32_e32 v99, v99, v27
	v_mul_f32_e32 v100, v100, v28
	v_mul_f32_e32 v101, v101, v29
	v_mul_f32_e32 v102, v102, v30
	v_mul_f32_e32 v103, v103, v31
	v_cvt_pk_bf16_f32 v96, v96, v97
	v_cvt_pk_bf16_f32 v97, v98, v99
	v_cvt_pk_bf16_f32 v98, v100, v101
	v_cvt_pk_bf16_f32 v99, v102, v103
	global_store_dwordx4 v21, v[96:99], s[36:37]
